# v36 + nt on the PEER-select phase's read-once pq fragment loads
# baseline (speedup 1.0000x reference)
; __device__ __forceinline__ f32x16 mfma32(bf16x8 a, bf16x8 b, f32x16 c) { return __builtin_amdgcn_mfma_f32_32x32x16_bf16(a, b, c, 0, 0, 0); }
; __device__ __forceinline__ int accrow(int reg, int hh) { return (reg & 3) + 8 * (reg >> 2) + 4 * hh; }
; __device__ void phase_peer_select(const Params& p, char* lds) {
;     ...
;     {
;       const int c = wid >> 1;
;       f32x16 acc[2][2]; zero_acc(acc);
;       const bf16_t* ap = pq + (size_t)(t0 + l31) * LDH + h * 128 + c * 64 + hh * 8;
;       const bf16_t* bp = keys + ((size_t)((h * 2 + c) * 128 + (wid & 1) * 64 + l31)) * 64 + hh * 8;
; #pragma unroll
;       for (int ks = 0; ks < 4; ++ks) {
;         bf16x8 a0 = *(const bf16x8*)(ap + ks * 16), a1 = *(const bf16x8*)(ap + 32 * LDH + ks * 16);
;         bf16x8 b0 = *(const bf16x8*)(bp + ks * 16), b1 = *(const bf16x8*)(bp + 32 * 64 + ks * 16);
;         acc[0][0] = mfma32(a0, b0, acc[0][0]); acc[0][1] = mfma32(a0, b1, acc[0][1]);
;         acc[1][0] = mfma32(a1, b0, acc[1][0]); acc[1][1] = mfma32(a1, b1, acc[1][1]);
;       }
; #pragma unroll
;       for (int i = 0; i < 2; ++i)
; #pragma unroll
;         for (int j = 0; j < 2; ++j)
; #pragma unroll
;           for (int r = 0; r < 16; ++r) S[(i * 32 + accrow(r, hh)) * 260 + c * 128 + (wid & 1) * 64 + j * 32 + l31] = acc[i][j][r];
;     }
;     __syncthreads();
.LBB0_1094:
	s_and_b32 s41, s3, 0xffffffc0
	s_and_b32 s37, s36, 7
	v_or_b32_e32 v2, s41, v189
	v_mov_b64_e32 v[0:1], s[84:85]
	s_movk_i32 s0, 0x880
	v_mad_i64_i32 v[0:1], s[0:1], v2, s0, v[0:1]
	s_lshl_b32 s34, s37, 8
	v_lshl_add_u64 v[0:1], v[0:1], 0, s[34:35]
	v_lshl_add_u64 v[0:1], v[0:1], 0, v[182:183]
	v_mov_b32_e32 v67, v183
	s_lshl_b32 s0, s37, 14
	v_lshl_add_u64 v[178:179], v[0:1], 0, v[66:67]
	v_add_lshl_u32 v0, s0, v76, 1
	v_mov_b32_e32 v1, v183
	s_mov_b32 s0, 0x11000
	v_lshl_add_u64 v[186:187], v[64:65], 0, v[0:1]
	global_load_dwordx4 v[0:3], v[178:179], off nt
	v_add_co_u32_e32 v202, vcc, s0, v178
	s_movk_i32 s0, 0x1000
	s_nop 0
	v_addc_co_u32_e32 v203, vcc, 0, v179, vcc
	v_add_co_u32_e32 v204, vcc, s0, v186
	global_load_dwordx4 v[16:19], v[202:203], off nt
	global_load_dwordx4 v[4:7], v[186:187], off
	v_addc_co_u32_e32 v205, vcc, 0, v187, vcc
	global_load_dwordx4 v[20:23], v[204:205], off
	global_load_dwordx4 v[174:177], v[178:179], off offset:32 nt
	global_load_dwordx4 v[190:193], v[202:203], off offset:32 nt
	global_load_dwordx4 v[194:197], v[186:187], off offset:32
	global_load_dwordx4 v[198:201], v[204:205], off offset:32
	global_load_dwordx4 v[208:211], v[178:179], off offset:64 nt
	global_load_dwordx4 v[212:215], v[202:203], off offset:64 nt
	global_load_dwordx4 v[216:219], v[186:187], off offset:64
	global_load_dwordx4 v[232:235], v[204:205], off offset:64
	s_waitcnt vmcnt(9)
	v_mfma_f32_32x32x16_bf16 v[32:47], v[0:3], v[4:7], 0
	s_waitcnt vmcnt(8)
	v_mfma_f32_32x32x16_bf16 v[48:63], v[0:3], v[20:23], 0
	v_mfma_f32_32x32x16_bf16 v[0:15], v[16:19], v[4:7], 0
	v_mfma_f32_32x32x16_bf16 v[16:31], v[16:19], v[20:23], 0
	s_waitcnt vmcnt(5)
	v_mfma_f32_32x32x16_bf16 v[32:47], v[174:177], v[194:197], v[32:47]
	s_waitcnt vmcnt(4)
	v_mfma_f32_32x32x16_bf16 v[48:63], v[174:177], v[198:201], v[48:63]
	v_mfma_f32_32x32x16_bf16 v[0:15], v[190:193], v[194:197], v[0:15]
	v_mfma_f32_32x32x16_bf16 v[16:31], v[190:193], v[198:201], v[16:31]
	global_load_dwordx4 v[174:177], v[178:179], off offset:96 nt
	global_load_dwordx4 v[190:193], v[202:203], off offset:96 nt
	global_load_dwordx4 v[194:197], v[186:187], off offset:96
	global_load_dwordx4 v[198:201], v[204:205], off offset:96
	s_waitcnt vmcnt(5)
	v_mfma_f32_32x32x16_bf16 v[32:47], v[208:211], v[216:219], v[32:47]
	s_waitcnt vmcnt(4)
	v_mfma_f32_32x32x16_bf16 v[48:63], v[208:211], v[232:235], v[48:63]
	v_mfma_f32_32x32x16_bf16 v[0:15], v[212:215], v[216:219], v[0:15]
	v_mfma_f32_32x32x16_bf16 v[16:31], v[212:215], v[232:235], v[16:31]
	s_waitcnt vmcnt(1)
	v_mfma_f32_32x32x16_bf16 v[32:47], v[174:177], v[194:197], v[32:47]
	s_waitcnt vmcnt(0)
	v_mfma_f32_32x32x16_bf16 v[48:63], v[174:177], v[198:201], v[48:63]
	v_mfma_f32_32x32x16_bf16 v[0:15], v[190:193], v[194:197], v[0:15]
	v_mfma_f32_32x32x16_bf16 v[16:31], v[190:193], v[198:201], v[16:31]
	s_nop 9
	ds_write2_b32 v77, v32, v48 offset1:32
	ds_write2_b32 v142, v33, v49 offset0:4 offset1:36
	ds_write2_b32 v143, v34, v50 offset0:8 offset1:40
	ds_write2_b32 v144, v35, v51 offset0:12 offset1:44
	ds_write2_b32 v145, v36, v52 offset0:32 offset1:64
	ds_write2_b32 v146, v37, v53 offset0:36 offset1:68
	ds_write2_b32 v147, v38, v54 offset0:40 offset1:72
	ds_write2_b32 v148, v39, v55 offset0:44 offset1:76
	ds_write2_b32 v149, v40, v56 offset0:64 offset1:96
	ds_write2_b32 v150, v41, v57 offset0:68 offset1:100
	ds_write2_b32 v151, v42, v58 offset0:72 offset1:104
	ds_write2_b32 v152, v43, v59 offset0:76 offset1:108
	ds_write2_b32 v153, v44, v60 offset0:96 offset1:128
	ds_write2_b32 v154, v45, v61 offset0:100 offset1:132
	ds_write2_b32 v155, v46, v62 offset0:104 offset1:136
	ds_write2_b32 v156, v47, v63 offset0:108 offset1:140
	ds_write2_b32 v157, v0, v16 offset0:128 offset1:160
	ds_write2_b32 v158, v1, v17 offset0:132 offset1:164
	ds_write2_b32 v159, v2, v18 offset0:136 offset1:168
	ds_write2_b32 v160, v3, v19 offset0:140 offset1:172
	ds_write2_b32 v161, v4, v20 offset0:160 offset1:192
	ds_write2_b32 v162, v5, v21 offset0:164 offset1:196
	ds_write2_b32 v163, v6, v22 offset0:168 offset1:200
	ds_write2_b32 v164, v7, v23 offset0:172 offset1:204
	ds_write2_b32 v165, v8, v24 offset0:192 offset1:224
	ds_write2_b32 v166, v9, v25 offset0:196 offset1:228
	ds_write2_b32 v167, v10, v26 offset0:200 offset1:232
	ds_write2_b32 v168, v11, v27 offset0:204 offset1:236
	ds_write2_b32 v169, v12, v28 offset0:96 offset1:128
	ds_write2_b32 v170, v13, v29 offset0:100 offset1:132
	ds_write2_b32 v171, v14, v30 offset0:104 offset1:136
	ds_write2_b32 v172, v15, v31 offset0:108 offset1:140
	s_waitcnt lgkmcnt(0)
	s_barrier
; __device__ __forceinline__ unsigned fkey(float f) { unsigned u = __float_as_uint(f); return (u & 0x80000000u) ? ~u : (u | 0x80000000u); }
; __device__ __forceinline__ float fkey_inv(unsigned k) { unsigned u = (k & 0x80000000u) ? (k & 0x7fffffffu) : ~k; return __uint_as_float(u); }
; __device__ __forceinline__ void insert16(unsigned (&L)[16], unsigned x) {
; #pragma unroll
;   for (int i = 0; i < 16; ++i) { const unsigned hi = x > L[i] ? x : L[i]; x = x > L[i] ? L[i] : x; L[i] = hi; }
; }
; __device__ __forceinline__ void sort16_desc(unsigned (&a)[16]) {
; #pragma unroll
;   for (int k = 2; k <= 16; k <<= 1)
; #pragma unroll
;     for (int j = k >> 1; j > 0; j >>= 1)
; #pragma unroll
;       for (int i = 0; i < 16; ++i) {
;         const int l = i ^ j;
;         if (l > i) { if ((i & k) == 0) cswap_desc(a[i], a[l]); else cswap_desc(a[l], a[i]); }
;       }
; __device__ void phase_peer_select(const Params& p, char* lds) {
;     ...
;       const float* sp = S + tok * 260 + c * 128 + half * 64;
; #pragma unroll
;       for (int grp = 0; grp < 4; ++grp) {
;         unsigned G[16];
; #pragma unroll
;         for (int n4 = 0; n4 < 4; ++n4) {
;           const f32x4 v = *(const f32x4*)(sp + grp * 16 + n4 * 4);
;           const unsigned ib = (unsigned)(127 - (half * 64 + grp * 16 + n4 * 4));
; #pragma unroll
;           for (int e = 0; e < 4; ++e) G[n4 * 4 + e] = (fkey(v[e]) & ~127u) | (ib - e);
;         }
;         sort16_desc(G);
	ds_read_b128 v[0:3], v72
	ds_read_b128 v[4:7], v72 offset:16
	ds_read_b128 v[8:11], v72 offset:32
	ds_read_b128 v[12:15], v72 offset:48
	ds_read_b128 v[24:27], v72 offset:64
	s_waitcnt lgkmcnt(4)
	v_not_b32_e32 v16, v0
	v_or_b32_e32 v17, 0x80000000, v0
	v_cmp_gt_i32_e32 vcc, 0, v0
	s_waitcnt lgkmcnt(0)
	v_not_b32_e32 v28, v24
	v_cndmask_b32_e32 v0, v17, v16, vcc
	v_not_b32_e32 v16, v1
	v_or_b32_e32 v17, 0x80000000, v1
	v_cmp_gt_i32_e32 vcc, 0, v1
	v_not_b32_e32 v29, v27
	v_and_or_b32 v0, v0, s38, v78
	v_cndmask_b32_e32 v1, v17, v16, vcc
	v_not_b32_e32 v16, v2
	v_or_b32_e32 v17, 0x80000000, v2
	v_cmp_gt_i32_e32 vcc, 0, v2
	v_and_or_b32 v1, v1, s38, v79
	s_nop 0
	v_cndmask_b32_e32 v2, v17, v16, vcc
	v_not_b32_e32 v16, v3
	v_or_b32_e32 v17, 0x80000000, v3
	v_cmp_gt_i32_e32 vcc, 0, v3
	v_and_or_b32 v2, v2, s38, v80
	s_nop 0
	v_cndmask_b32_e32 v3, v17, v16, vcc
	v_not_b32_e32 v16, v4
	v_or_b32_e32 v17, 0x80000000, v4
	v_cmp_gt_i32_e32 vcc, 0, v4
	v_and_or_b32 v3, v3, s38, v81
	s_nop 0
	v_cndmask_b32_e32 v4, v17, v16, vcc
	v_not_b32_e32 v16, v5
	v_or_b32_e32 v17, 0x80000000, v5
	v_cmp_gt_i32_e32 vcc, 0, v5
	v_and_or_b32 v4, v4, s38, v82
	s_nop 0
	v_cndmask_b32_e32 v5, v17, v16, vcc
	v_not_b32_e32 v16, v6
	v_or_b32_e32 v17, 0x80000000, v6
	v_cmp_gt_i32_e32 vcc, 0, v6
	v_and_or_b32 v5, v5, s38, v83
	s_nop 0
	v_cndmask_b32_e32 v6, v17, v16, vcc
	v_not_b32_e32 v16, v7
	v_or_b32_e32 v17, 0x80000000, v7
	v_cmp_gt_i32_e32 vcc, 0, v7
	v_and_or_b32 v6, v6, s38, v84
	s_nop 0
	v_cndmask_b32_e32 v7, v17, v16, vcc
	v_not_b32_e32 v16, v8
	v_or_b32_e32 v17, 0x80000000, v8
	v_cmp_gt_i32_e32 vcc, 0, v8
	v_and_or_b32 v7, v7, s38, v85
	s_nop 0
	v_cndmask_b32_e32 v8, v17, v16, vcc
	v_not_b32_e32 v16, v9
	v_or_b32_e32 v17, 0x80000000, v9
	v_cmp_gt_i32_e32 vcc, 0, v9
	v_and_or_b32 v8, v8, s38, v86
	s_nop 0
	v_cndmask_b32_e32 v9, v17, v16, vcc
	v_not_b32_e32 v16, v10
	v_or_b32_e32 v17, 0x80000000, v10
	v_cmp_gt_i32_e32 vcc, 0, v10
	v_and_or_b32 v9, v9, s38, v87
	s_nop 0
	v_cndmask_b32_e32 v10, v17, v16, vcc
	v_not_b32_e32 v16, v11
	v_or_b32_e32 v17, 0x80000000, v11
	v_cmp_gt_i32_e32 vcc, 0, v11
	v_and_or_b32 v10, v10, s38, v88
	s_nop 0
	v_cndmask_b32_e32 v11, v17, v16, vcc
	v_not_b32_e32 v16, v12
	v_or_b32_e32 v17, 0x80000000, v12
	v_cmp_gt_i32_e32 vcc, 0, v12
	v_and_or_b32 v11, v11, s38, v89
	s_nop 0
	v_cndmask_b32_e32 v12, v17, v16, vcc
	v_not_b32_e32 v16, v13
	v_or_b32_e32 v17, 0x80000000, v13
	v_cmp_gt_i32_e32 vcc, 0, v13
	v_and_or_b32 v12, v12, s38, v90
	s_nop 0
	v_cndmask_b32_e32 v13, v17, v16, vcc
	v_not_b32_e32 v16, v14
	v_or_b32_e32 v17, 0x80000000, v14
	v_cmp_gt_i32_e32 vcc, 0, v14
	v_and_or_b32 v13, v13, s38, v91
	s_nop 0
	v_cndmask_b32_e32 v14, v17, v16, vcc
	v_not_b32_e32 v16, v15
	v_or_b32_e32 v17, 0x80000000, v15
	v_cmp_gt_i32_e32 vcc, 0, v15
	v_and_or_b32 v14, v14, s38, v92
	s_nop 0
	v_cndmask_b32_e32 v15, v17, v16, vcc
	v_cmp_gt_i32_e32 vcc, 0, v24
	v_or_b32_e32 v24, 0x80000000, v24
	v_and_or_b32 v15, v15, s38, v93
	v_cndmask_b32_e32 v24, v24, v28, vcc
	v_cmp_gt_i32_e32 vcc, 0, v25
	v_not_b32_e32 v28, v25
	v_or_b32_e32 v25, 0x80000000, v25
	v_cndmask_b32_e32 v25, v25, v28, vcc
	v_cmp_gt_i32_e32 vcc, 0, v27
	v_or_b32_e32 v27, 0x80000000, v27
	v_and_or_b32 v24, v24, s38, v94
	v_cndmask_b32_e32 v27, v27, v29, vcc
	v_cmp_gt_i32_e32 vcc, 0, v26
	v_not_b32_e32 v29, v26
	v_or_b32_e32 v26, 0x80000000, v26
	v_cndmask_b32_e32 v26, v26, v29, vcc
	v_and_or_b32 v25, v25, s38, v95
	v_and_or_b32 v27, v27, s38, v96
	v_and_or_b32 v26, v26, s38, v97
	v_max_u32_e32 v28, v24, v25
	v_min_u32_e32 v29, v27, v26
	v_min_u32_e32 v31, v24, v25
	v_max_u32_e32 v32, v27, v26
	ds_read_b128 v[24:27], v72 offset:80
	v_max_u32_e32 v30, v28, v29
	v_max_u32_e32 v33, v31, v32
	v_max_u32_e32 v34, v30, v33
	v_min_u32_e32 v30, v30, v33
	s_waitcnt lgkmcnt(0)
	v_cmp_gt_i32_e32 vcc, 0, v27
	v_not_b32_e32 v35, v27
	v_or_b32_e32 v27, 0x80000000, v27
	v_cndmask_b32_e32 v27, v27, v35, vcc
	v_cmp_gt_i32_e32 vcc, 0, v26
	v_not_b32_e32 v35, v26
	v_or_b32_e32 v26, 0x80000000, v26
	v_cndmask_b32_e32 v26, v26, v35, vcc
	v_cmp_gt_i32_e32 vcc, 0, v24
	v_not_b32_e32 v36, v24
	v_or_b32_e32 v24, 0x80000000, v24
	v_cndmask_b32_e32 v24, v24, v36, vcc
	v_cmp_gt_i32_e32 vcc, 0, v25
	v_not_b32_e32 v36, v25
	v_or_b32_e32 v25, 0x80000000, v25
	v_cndmask_b32_e32 v25, v25, v36, vcc
	v_and_or_b32 v27, v27, s38, v98
	v_and_or_b32 v26, v26, s38, v99
	v_and_or_b32 v24, v24, s38, v100
	v_and_or_b32 v25, v25, s38, v101
	v_max_u32_e32 v35, v27, v26
	v_min_u32_e32 v36, v24, v25
	v_min_u32_e32 v26, v27, v26
	v_max_u32_e32 v24, v24, v25
	v_min_u32_e32 v37, v35, v36
	v_min_u32_e32 v25, v26, v24
	v_min_u32_e32 v27, v28, v29
	v_min_u32_e32 v28, v31, v32
	v_max_u32_e32 v31, v35, v36
	v_max_u32_e32 v24, v26, v24
	v_min_u32_e32 v38, v37, v25
	v_max_u32_e32 v29, v27, v28
	v_min_u32_e32 v32, v31, v24
	v_max_u32_e32 v33, v37, v25
	v_min_u32_e32 v28, v27, v28
	v_max_u32_e32 v31, v31, v24
	ds_read_b128 v[24:27], v72 offset:112
	v_max_u32_e32 v16, v0, v1
	v_min_u32_e32 v0, v0, v1
	v_max_u32_e32 v1, v3, v2
	v_min_u32_e32 v2, v3, v2
	s_waitcnt lgkmcnt(0)
	v_cmp_gt_i32_e32 vcc, 0, v27
	v_not_b32_e32 v43, v27
	v_or_b32_e32 v27, 0x80000000, v27
	v_cndmask_b32_e32 v27, v27, v43, vcc
	v_cmp_gt_i32_e32 vcc, 0, v26
	v_not_b32_e32 v43, v26
	v_or_b32_e32 v26, 0x80000000, v26
	v_cndmask_b32_e32 v26, v26, v43, vcc
	v_cmp_gt_i32_e32 vcc, 0, v24
	v_not_b32_e32 v44, v24
	v_or_b32_e32 v24, 0x80000000, v24
	v_cndmask_b32_e32 v24, v24, v44, vcc
	v_cmp_gt_i32_e32 vcc, 0, v25
	v_not_b32_e32 v44, v25
	v_or_b32_e32 v25, 0x80000000, v25
	v_cndmask_b32_e32 v25, v25, v44, vcc
	v_and_or_b32 v27, v27, s38, v102
	v_and_or_b32 v26, v26, s38, v103
	v_and_or_b32 v24, v24, s38, v104
	v_and_or_b32 v25, v25, s38, v105
	v_max_u32_e32 v43, v27, v26
	v_min_u32_e32 v44, v24, v25
	v_min_u32_e32 v46, v27, v26
	v_max_u32_e32 v47, v24, v25
	ds_read_b128 v[24:27], v72 offset:96
	v_max_u32_e32 v3, v4, v5
	v_min_u32_e32 v4, v4, v5
	v_max_u32_e32 v5, v7, v6
	v_min_u32_e32 v6, v7, v6
	s_waitcnt lgkmcnt(0)
; __device__ __forceinline__ unsigned fkey(float f) { unsigned u = __float_as_uint(f); return (u & 0x80000000u) ? ~u : (u | 0x80000000u); }
; __device__ __forceinline__ void sort16_desc(unsigned (&a)[16]) {
; #pragma unroll
;   for (int k = 2; k <= 16; k <<= 1)
; #pragma unroll
;     for (int j = k >> 1; j > 0; j >>= 1)
; #pragma unroll
;       for (int i = 0; i < 16; ++i) {
;         const int l = i ^ j;
;         if (l > i) { if ((i & k) == 0) cswap_desc(a[i], a[l]); else cswap_desc(a[l], a[i]); }
;       }
; __device__ void phase_peer_select(const Params& p, char* lds) {
;     ...
;       const float* sp = S + tok * 260 + c * 128 + half * 64;
; #pragma unroll
;       for (int grp = 0; grp < 4; ++grp) {
;         unsigned G[16];
; #pragma unroll
;         for (int n4 = 0; n4 < 4; ++n4) {
;           const f32x4 v = *(const f32x4*)(sp + grp * 16 + n4 * 4);
;           const unsigned ib = (unsigned)(127 - (half * 64 + grp * 16 + n4 * 4));
; #pragma unroll
;           for (int e = 0; e < 4; ++e) G[n4 * 4 + e] = (fkey(v[e]) & ~127u) | (ib - e);
;         }
;         sort16_desc(G);
;         if (grp == 0) {
; #pragma unroll
;           for (int i = 0; i < 16; ++i) L[i] = G[i];
;         } else merge16_desc<true>(L, G);
	v_cmp_gt_i32_e32 vcc, 0, v24
	v_not_b32_e32 v50, v24
	v_or_b32_e32 v24, 0x80000000, v24
	v_cndmask_b32_e32 v24, v24, v50, vcc
	v_cmp_gt_i32_e32 vcc, 0, v25
	v_not_b32_e32 v50, v25
	v_or_b32_e32 v25, 0x80000000, v25
	v_cndmask_b32_e32 v25, v25, v50, vcc
	v_cmp_gt_i32_e32 vcc, 0, v27
	v_not_b32_e32 v51, v27
	v_or_b32_e32 v27, 0x80000000, v27
	v_cndmask_b32_e32 v27, v27, v51, vcc
	v_cmp_gt_i32_e32 vcc, 0, v26
	v_not_b32_e32 v51, v26
	v_or_b32_e32 v26, 0x80000000, v26
	v_cndmask_b32_e32 v26, v26, v51, vcc
	v_and_or_b32 v24, v24, s38, v106
	v_and_or_b32 v25, v25, s38, v107
	v_and_or_b32 v27, v27, s38, v108
	v_and_or_b32 v26, v26, s38, v109
	v_max_u32_e32 v7, v8, v9
	v_min_u32_e32 v8, v8, v9
	v_max_u32_e32 v9, v11, v10
	v_min_u32_e32 v10, v11, v10
	v_max_u32_e32 v11, v12, v13
	v_min_u32_e32 v12, v12, v13
	v_max_u32_e32 v13, v15, v14
	v_min_u32_e32 v14, v15, v14
	v_max_u32_e32 v50, v24, v25
	v_min_u32_e32 v51, v27, v26
	v_min_u32_e32 v24, v24, v25
	v_max_u32_e32 v25, v27, v26
	v_max_u32_e32 v15, v16, v2
	v_min_u32_e32 v2, v16, v2
	v_max_u32_e32 v16, v0, v1
	v_min_u32_e32 v0, v0, v1
	v_max_u32_e32 v1, v6, v3
	v_min_u32_e32 v3, v6, v3
	v_max_u32_e32 v6, v5, v4
	v_min_u32_e32 v4, v5, v4
	v_max_u32_e32 v5, v7, v10
	v_min_u32_e32 v7, v7, v10
	v_max_u32_e32 v10, v8, v9
	v_min_u32_e32 v8, v8, v9
	v_max_u32_e32 v9, v14, v11
	v_min_u32_e32 v11, v14, v11
	v_max_u32_e32 v14, v13, v12
	v_min_u32_e32 v12, v13, v12
	v_max_u32_e32 v45, v43, v44
	v_max_u32_e32 v48, v46, v47
	v_min_u32_e32 v52, v50, v51
	v_min_u32_e32 v26, v24, v25
	v_min_u32_e32 v43, v43, v44
	v_min_u32_e32 v44, v46, v47
	v_max_u32_e32 v47, v50, v51
	v_max_u32_e32 v24, v24, v25
	v_max_u32_e32 v13, v15, v16
	v_min_u32_e32 v15, v15, v16
	v_max_u32_e32 v16, v2, v0
	v_min_u32_e32 v0, v2, v0
	v_max_u32_e32 v2, v4, v3
	v_min_u32_e32 v3, v4, v3
	v_max_u32_e32 v4, v6, v1
	v_min_u32_e32 v1, v6, v1
	v_max_u32_e32 v6, v5, v10
	v_min_u32_e32 v5, v5, v10
	v_max_u32_e32 v10, v7, v8
	v_min_u32_e32 v7, v7, v8
	v_max_u32_e32 v8, v12, v11
	v_min_u32_e32 v11, v12, v11
	v_max_u32_e32 v12, v14, v9
	v_min_u32_e32 v9, v14, v9
	v_max_u32_e32 v49, v45, v48
	v_min_u32_e32 v27, v52, v26
	v_max_u32_e32 v46, v43, v44
	v_min_u32_e32 v25, v47, v24
	v_min_u32_e32 v45, v45, v48
	v_max_u32_e32 v26, v52, v26
	v_min_u32_e32 v43, v43, v44
	v_max_u32_e32 v24, v47, v24
	v_max_u32_e32 v14, v13, v3
	v_min_u32_e32 v3, v13, v3
	v_max_u32_e32 v13, v15, v2
	v_min_u32_e32 v2, v15, v2
	v_max_u32_e32 v15, v16, v1
	v_min_u32_e32 v1, v16, v1
	v_max_u32_e32 v16, v0, v4
	v_min_u32_e32 v0, v0, v4
	v_max_u32_e32 v4, v11, v6
	v_min_u32_e32 v6, v11, v6
	v_max_u32_e32 v11, v8, v5
	v_min_u32_e32 v5, v8, v5
	v_max_u32_e32 v8, v9, v10
	v_min_u32_e32 v9, v9, v10
	v_max_u32_e32 v10, v12, v7
	v_min_u32_e32 v7, v12, v7
	v_max_u32_e32 v39, v34, v38
	v_max_u32_e32 v35, v29, v32
	v_max_u32_e32 v37, v30, v33
	v_max_u32_e32 v40, v28, v31
	v_min_u32_e32 v53, v49, v27
	v_min_u32_e32 v50, v46, v25
	v_min_u32_e32 v48, v45, v26
	v_min_u32_e32 v44, v43, v24
	v_min_u32_e32 v34, v34, v38
	v_min_u32_e32 v29, v29, v32
	v_min_u32_e32 v30, v30, v33
	v_min_u32_e32 v28, v28, v31
	v_max_u32_e32 v27, v49, v27
	v_max_u32_e32 v25, v46, v25
	v_max_u32_e32 v26, v45, v26
	v_max_u32_e32 v24, v43, v24
	v_max_u32_e32 v12, v14, v15
	v_min_u32_e32 v14, v14, v15
	v_max_u32_e32 v15, v13, v16
	v_min_u32_e32 v13, v13, v16
	v_max_u32_e32 v16, v3, v1
	v_min_u32_e32 v1, v3, v1
	v_max_u32_e32 v3, v2, v0
	v_min_u32_e32 v0, v2, v0
	v_max_u32_e32 v2, v9, v6
	v_min_u32_e32 v6, v9, v6
	v_max_u32_e32 v9, v7, v5
	v_min_u32_e32 v5, v7, v5
	v_max_u32_e32 v7, v8, v4
	v_min_u32_e32 v4, v8, v4
	v_max_u32_e32 v8, v10, v11
	v_min_u32_e32 v10, v10, v11
	v_max_u32_e32 v36, v39, v35
	v_max_u32_e32 v41, v37, v40
	v_min_u32_e32 v51, v53, v50
	v_min_u32_e32 v47, v48, v44
	v_max_u32_e32 v32, v34, v29
	v_max_u32_e32 v31, v30, v28
	v_min_u32_e32 v38, v27, v25
	v_min_u32_e32 v43, v26, v24
	v_min_u32_e32 v35, v39, v35
	v_min_u32_e32 v37, v37, v40
	v_max_u32_e32 v40, v53, v50
	v_max_u32_e32 v44, v48, v44
	v_min_u32_e32 v29, v34, v29
	v_min_u32_e32 v28, v30, v28
	v_max_u32_e32 v25, v27, v25
	v_max_u32_e32 v24, v26, v24
	v_max_u32_e32 v11, v12, v15
	v_min_u32_e32 v12, v12, v15
	v_max_u32_e32 v15, v14, v13
	v_min_u32_e32 v13, v14, v13
	v_max_u32_e32 v14, v16, v3
	v_min_u32_e32 v3, v16, v3
	v_max_u32_e32 v16, v1, v0
	v_min_u32_e32 v0, v1, v0
	v_max_u32_e32 v1, v5, v6
	v_min_u32_e32 v5, v5, v6
	v_max_u32_e32 v6, v9, v2
	v_min_u32_e32 v2, v9, v2
	v_max_u32_e32 v9, v10, v4
	v_min_u32_e32 v4, v10, v4
	v_max_u32_e32 v10, v8, v7
	v_min_u32_e32 v7, v8, v7
	v_max_u32_e32 v42, v36, v41
	v_min_u32_e32 v52, v51, v47
	v_max_u32_e32 v33, v32, v31
	v_min_u32_e32 v45, v38, v43
	v_max_u32_e32 v39, v35, v37
	v_min_u32_e32 v48, v40, v44
	v_max_u32_e32 v30, v29, v28
	v_min_u32_e32 v26, v25, v24
	v_min_u32_e32 v36, v36, v41
	v_max_u32_e32 v41, v51, v47
	v_min_u32_e32 v31, v32, v31
	v_max_u32_e32 v32, v38, v43
	v_min_u32_e32 v35, v35, v37
	v_max_u32_e32 v37, v40, v44
	v_min_u32_e32 v28, v29, v28
	v_max_u32_e32 v24, v25, v24
	v_max_u32_e32 v8, v11, v5
	v_min_u32_e32 v5, v11, v5
	v_max_u32_e32 v11, v12, v1
	v_min_u32_e32 v1, v12, v1
	v_max_u32_e32 v12, v15, v2
	v_min_u32_e32 v2, v15, v2
	v_max_u32_e32 v15, v13, v6
	v_min_u32_e32 v6, v13, v6
	v_max_u32_e32 v13, v14, v4
	v_min_u32_e32 v4, v14, v4
	v_max_u32_e32 v14, v3, v9
	v_min_u32_e32 v3, v3, v9
	v_max_u32_e32 v9, v16, v7
	v_min_u32_e32 v7, v16, v7
	v_max_u32_e32 v16, v0, v10
	v_min_u32_e32 v0, v0, v10
	v_min_u32_e32 v54, v42, v52
	v_min_u32_e32 v46, v33, v45
	v_min_u32_e32 v50, v39, v48
	v_min_u32_e32 v27, v30, v26
	v_min_u32_e32 v47, v36, v41
	v_min_u32_e32 v38, v31, v32
	v_min_u32_e32 v40, v35, v37
; __device__ __forceinline__ unsigned fkey(float f) { unsigned u = __float_as_uint(f); return (u & 0x80000000u) ? ~u : (u | 0x80000000u); }
; __device__ __forceinline__ void sort16_desc(unsigned (&a)[16]) {
; #pragma unroll
;   for (int k = 2; k <= 16; k <<= 1)
; #pragma unroll
;     for (int j = k >> 1; j > 0; j >>= 1)
; #pragma unroll
;       for (int i = 0; i < 16; ++i) {
;         const int l = i ^ j;
;         if (l > i) { if ((i & k) == 0) cswap_desc(a[i], a[l]); else cswap_desc(a[l], a[i]); }
;       }
; }
; template <bool SORT>
; __device__ __forceinline__ void merge16_desc(unsigned (&a)[16], const unsigned (&b)[16]) {
; #pragma unroll
;   for (int i = 0; i < 16; ++i) a[i] = a[i] > b[15 - i] ? a[i] : b[15 - i];
;   if (SORT) {
; #pragma unroll
;     for (int j = 8; j > 0; j >>= 1)
; #pragma unroll
;       for (int i = 0; i < 16; ++i) { const int l = i ^ j; if (l > i) cswap_desc(a[i], a[l]); }
;   }
; __device__ void phase_peer_select(const Params& p, char* lds) {
;     ...
;       for (int grp = 0; grp < 4; ++grp) {
;         unsigned G[16];
; #pragma unroll
;         for (int n4 = 0; n4 < 4; ++n4) {
;           const f32x4 v = *(const f32x4*)(sp + grp * 16 + n4 * 4);
;           const unsigned ib = (unsigned)(127 - (half * 64 + grp * 16 + n4 * 4));
; #pragma unroll
;           for (int e = 0; e < 4; ++e) G[n4 * 4 + e] = (fkey(v[e]) & ~127u) | (ib - e);
;         }
;         sort16_desc(G);
;         if (grp == 0) {
; #pragma unroll
;           for (int i = 0; i < 16; ++i) L[i] = G[i];
;         } else merge16_desc<true>(L, G);
	v_min_u32_e32 v25, v28, v24
	v_max_u32_e32 v42, v42, v52
	v_max_u32_e32 v33, v33, v45
	v_max_u32_e32 v39, v39, v48
	v_max_u32_e32 v26, v30, v26
	v_max_u32_e32 v36, v36, v41
	v_max_u32_e32 v31, v31, v32
	v_max_u32_e32 v35, v35, v37
	v_max_u32_e32 v24, v28, v24
	v_max_u32_e32 v10, v8, v13
	v_min_u32_e32 v13, v8, v13
	v_max_u32_e32 v8, v11, v14
	v_min_u32_e32 v11, v11, v14
	v_max_u32_e32 v14, v12, v9
	v_min_u32_e32 v9, v12, v9
	v_max_u32_e32 v17, v15, v16
	v_min_u32_e32 v15, v15, v16
	v_max_u32_e32 v16, v5, v4
	v_min_u32_e32 v18, v5, v4
	v_max_u32_e32 v19, v1, v3
	v_min_u32_e32 v20, v1, v3
	v_max_u32_e32 v3, v2, v7
	v_min_u32_e32 v21, v2, v7
	v_min_u32_e32 v22, v6, v0
	v_min_u32_e32 v49, v54, v46
	v_min_u32_e32 v34, v50, v27
	v_min_u32_e32 v43, v47, v38
	v_min_u32_e32 v29, v40, v25
	v_max_u32_e32 v46, v54, v46
	v_max_u32_e32 v27, v50, v27
	v_max_u32_e32 v38, v47, v38
	v_max_u32_e32 v25, v40, v25
	v_min_u32_e32 v45, v42, v33
	v_min_u32_e32 v30, v39, v26
	v_min_u32_e32 v32, v36, v31
	v_min_u32_e32 v28, v35, v24
	v_max_u32_e32 v33, v42, v33
	v_max_u32_e32 v26, v39, v26
	v_max_u32_e32 v31, v36, v31
	v_max_u32_e32 v24, v35, v24
	v_max_u32_e32 v7, v6, v0
	v_max_u32_e32 v5, v13, v9
	v_min_u32_e32 v1, v13, v9
	v_max_u32_e32 v13, v11, v15
	v_min_u32_e32 v9, v11, v15
	v_max_u32_e32 v6, v16, v3
	v_min_u32_e32 v2, v16, v3
	v_min_u32_e32 v3, v18, v21
	v_min_u32_e32 v11, v20, v22
	v_min_u32_e32 v53, v49, v34
	v_max_u32_e32 v34, v49, v34
	v_min_u32_e32 v49, v46, v27
	v_min_u32_e32 v40, v38, v25
	v_max_u32_e32 v27, v46, v27
	v_max_u32_e32 v25, v38, v25
	v_min_u32_e32 v39, v33, v26
	v_min_u32_e32 v35, v31, v24
	v_max_u32_e32 v26, v33, v26
	v_max_u32_e32 v24, v31, v24
	v_max_u32_e32 v15, v20, v22
	v_min_u32_e32 v20, v1, v9
	v_min_u32_e32 v16, v3, v11
	v_min_u32_e32 v38, v27, v25
	v_min_u32_e32 v31, v26, v24
	v_max3_u32 v1, v1, v9, v38
	v_max3_u32 v9, v20, v27, v25
	v_max3_u32 v3, v3, v11, v31
	v_max3_u32 v11, v16, v26, v24
	ds_read_b128 v[24:27], v72 offset:128
	v_max_u32_e32 v4, v10, v14
	v_min_u32_e32 v0, v10, v14
	v_min_u32_e32 v10, v19, v7
	v_min_u32_e32 v46, v45, v30
	v_min_u32_e32 v37, v32, v28
	v_max_u32_e32 v30, v45, v30
	v_max_u32_e32 v28, v32, v28
	v_max_u32_e32 v14, v19, v7
	v_max_u32_e32 v7, v18, v21
	v_min_u32_e32 v18, v2, v10
	v_min_u32_e32 v32, v30, v28
	v_max_u32_e32 v12, v8, v17
	v_min_u32_e32 v8, v8, v17
	v_min_u32_e32 v44, v43, v29
	v_max_u32_e32 v29, v43, v29
	v_max3_u32 v2, v2, v10, v32
	v_max3_u32 v10, v18, v30, v28
	s_waitcnt lgkmcnt(0)
	v_cmp_gt_i32_e32 vcc, 0, v24
	v_not_b32_e32 v28, v24
	v_or_b32_e32 v24, 0x80000000, v24
	v_min_u32_e32 v22, v0, v8
	v_min_u32_e32 v43, v34, v29
	v_cndmask_b32_e32 v24, v24, v28, vcc
	v_cmp_gt_i32_e32 vcc, 0, v25
	v_not_b32_e32 v28, v25
	v_or_b32_e32 v25, 0x80000000, v25
	v_max3_u32 v0, v0, v8, v43
	v_max3_u32 v8, v22, v34, v29
	v_cndmask_b32_e32 v25, v25, v28, vcc
	v_cmp_gt_i32_e32 vcc, 0, v27
	v_not_b32_e32 v29, v27
	v_or_b32_e32 v27, 0x80000000, v27
	v_cndmask_b32_e32 v27, v27, v29, vcc
	v_cmp_gt_i32_e32 vcc, 0, v26
	v_not_b32_e32 v29, v26
	v_or_b32_e32 v26, 0x80000000, v26
	v_cndmask_b32_e32 v26, v26, v29, vcc
	v_and_or_b32 v24, v24, s38, v110
	v_and_or_b32 v25, v25, s38, v111
	v_and_or_b32 v27, v27, s38, v112
	v_and_or_b32 v26, v26, s38, v113
	v_max_u32_e32 v28, v24, v25
	v_min_u32_e32 v29, v27, v26
	v_min_u32_e32 v31, v24, v25
	v_max_u32_e32 v32, v27, v26
	ds_read_b128 v[24:27], v72 offset:144
	v_min_u32_e32 v17, v7, v15
	v_min_u32_e32 v36, v39, v35
	v_max3_u32 v7, v7, v15, v36
	v_max3_u32 v15, v17, v39, v35
	s_waitcnt lgkmcnt(0)
	v_cmp_gt_i32_e32 vcc, 0, v27
	v_not_b32_e32 v35, v27
	v_or_b32_e32 v27, 0x80000000, v27
	v_cndmask_b32_e32 v27, v27, v35, vcc
	v_cmp_gt_i32_e32 vcc, 0, v26
	v_not_b32_e32 v35, v26
	v_or_b32_e32 v26, 0x80000000, v26
	v_cndmask_b32_e32 v26, v26, v35, vcc
	v_cmp_gt_i32_e32 vcc, 0, v24
	v_not_b32_e32 v36, v24
	v_or_b32_e32 v24, 0x80000000, v24
	v_cndmask_b32_e32 v24, v24, v36, vcc
	v_cmp_gt_i32_e32 vcc, 0, v25
	v_not_b32_e32 v36, v25
	v_or_b32_e32 v25, 0x80000000, v25
	v_cndmask_b32_e32 v25, v25, v36, vcc
	v_and_or_b32 v27, v27, s38, v114
	v_and_or_b32 v26, v26, s38, v115
	v_and_or_b32 v24, v24, s38, v116
	v_and_or_b32 v25, v25, s38, v117
	v_min_u32_e32 v19, v6, v14
	v_min_u32_e32 v41, v46, v37
	v_max_u32_e32 v35, v27, v26
	v_min_u32_e32 v36, v24, v25
	v_min_u32_e32 v26, v27, v26
	v_max_u32_e32 v24, v24, v25
	v_max3_u32 v6, v6, v14, v41
	v_max3_u32 v14, v19, v46, v37
	v_max_u32_e32 v30, v28, v29
	v_max_u32_e32 v33, v31, v32
	v_min_u32_e32 v37, v35, v36
	v_min_u32_e32 v25, v26, v24
	v_min_u32_e32 v27, v28, v29
	v_min_u32_e32 v28, v31, v32
	v_max_u32_e32 v31, v35, v36
	v_max_u32_e32 v24, v26, v24
	v_max_u32_e32 v34, v30, v33
	v_min_u32_e32 v38, v37, v25
	v_max_u32_e32 v29, v27, v28
	v_min_u32_e32 v32, v31, v24
	v_min_u32_e32 v30, v30, v33
	v_max_u32_e32 v33, v37, v25
	v_min_u32_e32 v28, v27, v28
	v_max_u32_e32 v31, v31, v24
	ds_read_b128 v[24:27], v72 offset:176
	v_min_u32_e32 v23, v4, v12
	v_min_u32_e32 v51, v53, v44
	v_max3_u32 v4, v4, v12, v51
	v_max3_u32 v12, v23, v53, v44
	s_waitcnt lgkmcnt(0)
	v_cmp_gt_i32_e32 vcc, 0, v27
	v_not_b32_e32 v43, v27
	v_or_b32_e32 v27, 0x80000000, v27
	v_cndmask_b32_e32 v27, v27, v43, vcc
	v_cmp_gt_i32_e32 vcc, 0, v26
	v_not_b32_e32 v43, v26
	v_or_b32_e32 v26, 0x80000000, v26
	v_cndmask_b32_e32 v26, v26, v43, vcc
	v_cmp_gt_i32_e32 vcc, 0, v24
	v_not_b32_e32 v44, v24
	v_or_b32_e32 v24, 0x80000000, v24
	v_cndmask_b32_e32 v24, v24, v44, vcc
	v_cmp_gt_i32_e32 vcc, 0, v25
	v_not_b32_e32 v44, v25
	v_or_b32_e32 v25, 0x80000000, v25
	v_cndmask_b32_e32 v25, v25, v44, vcc
	v_min_u32_e32 v47, v49, v40
	v_and_or_b32 v27, v27, s38, v118
	v_and_or_b32 v26, v26, s38, v119
	v_and_or_b32 v24, v24, s38, v120
	v_and_or_b32 v25, v25, s38, v121
	v_min_u32_e32 v21, v5, v13
	v_max3_u32 v5, v5, v13, v47
	v_max_u32_e32 v43, v27, v26
	v_min_u32_e32 v44, v24, v25
	v_min_u32_e32 v46, v27, v26
	v_max_u32_e32 v47, v24, v25
	ds_read_b128 v[24:27], v72 offset:160
	v_max_u32_e32 v45, v43, v44
	v_max_u32_e32 v48, v46, v47
	v_min_u32_e32 v43, v43, v44
	v_min_u32_e32 v44, v46, v47
	s_waitcnt lgkmcnt(0)
; __device__ __forceinline__ unsigned fkey(float f) { unsigned u = __float_as_uint(f); return (u & 0x80000000u) ? ~u : (u | 0x80000000u); }
; __device__ __forceinline__ void sort16_desc(unsigned (&a)[16]) {
; #pragma unroll
;   for (int k = 2; k <= 16; k <<= 1)
; #pragma unroll
;     for (int j = k >> 1; j > 0; j >>= 1)
; #pragma unroll
;       for (int i = 0; i < 16; ++i) {
;         const int l = i ^ j;
;         if (l > i) { if ((i & k) == 0) cswap_desc(a[i], a[l]); else cswap_desc(a[l], a[i]); }
;       }
; }
; template <bool SORT>
; __device__ __forceinline__ void merge16_desc(unsigned (&a)[16], const unsigned (&b)[16]) {
; #pragma unroll
;   for (int i = 0; i < 16; ++i) a[i] = a[i] > b[15 - i] ? a[i] : b[15 - i];
;   if (SORT) {
; #pragma unroll
;     for (int j = 8; j > 0; j >>= 1)
; #pragma unroll
;       for (int i = 0; i < 16; ++i) { const int l = i ^ j; if (l > i) cswap_desc(a[i], a[l]); }
;   }
; __device__ void phase_peer_select(const Params& p, char* lds) {
;     ...
;       for (int grp = 0; grp < 4; ++grp) {
;         unsigned G[16];
; #pragma unroll
;         for (int n4 = 0; n4 < 4; ++n4) {
;           const f32x4 v = *(const f32x4*)(sp + grp * 16 + n4 * 4);
;           const unsigned ib = (unsigned)(127 - (half * 64 + grp * 16 + n4 * 4));
; #pragma unroll
;           for (int e = 0; e < 4; ++e) G[n4 * 4 + e] = (fkey(v[e]) & ~127u) | (ib - e);
;         }
;         sort16_desc(G);
;         if (grp == 0) {
; #pragma unroll
;           for (int i = 0; i < 16; ++i) L[i] = G[i];
;         } else merge16_desc<true>(L, G);
	v_cmp_gt_i32_e32 vcc, 0, v24
	v_not_b32_e32 v50, v24
	v_or_b32_e32 v24, 0x80000000, v24
	v_cndmask_b32_e32 v24, v24, v50, vcc
	v_cmp_gt_i32_e32 vcc, 0, v25
	v_not_b32_e32 v50, v25
	v_or_b32_e32 v25, 0x80000000, v25
	v_cndmask_b32_e32 v25, v25, v50, vcc
	v_cmp_gt_i32_e32 vcc, 0, v27
	v_not_b32_e32 v51, v27
	v_or_b32_e32 v27, 0x80000000, v27
	v_cndmask_b32_e32 v27, v27, v51, vcc
	v_cmp_gt_i32_e32 vcc, 0, v26
	v_not_b32_e32 v51, v26
	v_or_b32_e32 v26, 0x80000000, v26
	v_cndmask_b32_e32 v26, v26, v51, vcc
	v_and_or_b32 v24, v24, s38, v122
	v_and_or_b32 v25, v25, s38, v123
	v_and_or_b32 v27, v27, s38, v124
	v_and_or_b32 v26, v26, s38, v125
	v_max_u32_e32 v50, v24, v25
	v_min_u32_e32 v51, v27, v26
	v_min_u32_e32 v24, v24, v25
	v_max_u32_e32 v25, v27, v26
	v_min_u32_e32 v52, v50, v51
	v_min_u32_e32 v26, v24, v25
	v_max_u32_e32 v47, v50, v51
	v_max_u32_e32 v24, v24, v25
	v_max3_u32 v13, v21, v49, v40
	v_max_u32_e32 v49, v45, v48
	v_min_u32_e32 v27, v52, v26
	v_max_u32_e32 v46, v43, v44
	v_min_u32_e32 v25, v47, v24
	v_min_u32_e32 v45, v45, v48
	v_max_u32_e32 v26, v52, v26
	v_min_u32_e32 v43, v43, v44
	v_max_u32_e32 v24, v47, v24
	v_max_u32_e32 v39, v34, v38
	v_max_u32_e32 v35, v29, v32
	v_max_u32_e32 v37, v30, v33
	v_max_u32_e32 v40, v28, v31
	v_min_u32_e32 v53, v49, v27
	v_min_u32_e32 v50, v46, v25
	v_min_u32_e32 v48, v45, v26
	v_min_u32_e32 v44, v43, v24
	v_min_u32_e32 v34, v34, v38
	v_min_u32_e32 v29, v29, v32
	v_min_u32_e32 v30, v30, v33
	v_min_u32_e32 v28, v28, v31
	v_max_u32_e32 v27, v49, v27
	v_max_u32_e32 v25, v46, v25
	v_max_u32_e32 v26, v45, v26
	v_max_u32_e32 v24, v43, v24
	v_max_u32_e32 v36, v39, v35
	v_max_u32_e32 v41, v37, v40
	v_min_u32_e32 v51, v53, v50
	v_min_u32_e32 v47, v48, v44
	v_max_u32_e32 v32, v34, v29
	v_max_u32_e32 v31, v30, v28
	v_min_u32_e32 v38, v27, v25
	v_min_u32_e32 v43, v26, v24
	v_min_u32_e32 v35, v39, v35
	v_min_u32_e32 v37, v37, v40
	v_max_u32_e32 v40, v53, v50
	v_max_u32_e32 v44, v48, v44
	v_min_u32_e32 v29, v34, v29
	v_min_u32_e32 v28, v30, v28
	v_max_u32_e32 v25, v27, v25
	v_max_u32_e32 v24, v26, v24
	v_max_u32_e32 v42, v36, v41
	v_min_u32_e32 v52, v51, v47
	v_max_u32_e32 v33, v32, v31
	v_min_u32_e32 v45, v38, v43
	v_max_u32_e32 v39, v35, v37
	v_min_u32_e32 v48, v40, v44
	v_max_u32_e32 v30, v29, v28
	v_min_u32_e32 v26, v25, v24
	v_min_u32_e32 v36, v36, v41
	v_max_u32_e32 v41, v51, v47
	v_min_u32_e32 v31, v32, v31
	v_max_u32_e32 v32, v38, v43
	v_min_u32_e32 v35, v35, v37
	v_max_u32_e32 v37, v40, v44
	v_min_u32_e32 v28, v29, v28
	v_max_u32_e32 v24, v25, v24
	v_max_u32_e32 v16, v4, v6
	v_min_u32_e32 v4, v4, v6
	v_max_u32_e32 v6, v12, v14
	v_min_u32_e32 v12, v12, v14
	v_max_u32_e32 v14, v0, v2
	v_min_u32_e32 v0, v0, v2
	v_max_u32_e32 v2, v8, v10
	v_min_u32_e32 v8, v8, v10
	v_max_u32_e32 v10, v5, v7
	v_min_u32_e32 v5, v5, v7
	v_max_u32_e32 v7, v13, v15
	v_min_u32_e32 v13, v13, v15
	v_max_u32_e32 v15, v1, v3
	v_min_u32_e32 v1, v1, v3
	v_max_u32_e32 v3, v9, v11
	v_min_u32_e32 v9, v9, v11
	v_min_u32_e32 v54, v42, v52
	v_min_u32_e32 v46, v33, v45
	v_min_u32_e32 v50, v39, v48
	v_min_u32_e32 v27, v30, v26
	v_min_u32_e32 v47, v36, v41
	v_min_u32_e32 v38, v31, v32
	v_min_u32_e32 v40, v35, v37
	v_min_u32_e32 v25, v28, v24
	v_max_u32_e32 v42, v42, v52
	v_max_u32_e32 v33, v33, v45
	v_max_u32_e32 v39, v39, v48
	v_max_u32_e32 v26, v30, v26
	v_max_u32_e32 v36, v36, v41
	v_max_u32_e32 v31, v31, v32
	v_max_u32_e32 v35, v35, v37
	v_max_u32_e32 v24, v28, v24
	v_max_u32_e32 v11, v16, v10
	v_min_u32_e32 v10, v16, v10
	v_max_u32_e32 v16, v6, v7
	v_min_u32_e32 v6, v6, v7
	v_max_u32_e32 v7, v14, v15
	v_min_u32_e32 v14, v14, v15
	v_max_u32_e32 v15, v2, v3
	v_min_u32_e32 v2, v2, v3
	v_max_u32_e32 v3, v4, v5
	v_min_u32_e32 v17, v4, v5
	v_min_u32_e32 v19, v12, v13
	v_max_u32_e32 v20, v0, v1
	v_min_u32_e32 v21, v0, v1
	v_min_u32_e32 v23, v8, v9
	v_min_u32_e32 v49, v54, v46
	v_min_u32_e32 v34, v50, v27
	v_min_u32_e32 v43, v47, v38
	v_min_u32_e32 v29, v40, v25
	v_max_u32_e32 v46, v54, v46
	v_max_u32_e32 v27, v50, v27
	v_max_u32_e32 v38, v47, v38
	v_max_u32_e32 v25, v40, v25
	v_min_u32_e32 v45, v42, v33
	v_min_u32_e32 v30, v39, v26
	v_min_u32_e32 v32, v36, v31
	v_min_u32_e32 v28, v35, v24
	v_max_u32_e32 v33, v42, v33
	v_max_u32_e32 v26, v39, v26
	v_max_u32_e32 v31, v36, v31
	v_max_u32_e32 v24, v35, v24
	v_max_u32_e32 v18, v12, v13
	v_max_u32_e32 v22, v8, v9
	v_max_u32_e32 v4, v11, v7
	v_min_u32_e32 v0, v11, v7
	v_min_u32_e32 v1, v10, v14
	v_max_u32_e32 v13, v6, v2
	v_min_u32_e32 v9, v6, v2
	v_max_u32_e32 v6, v3, v20
	v_min_u32_e32 v2, v3, v20
	v_min_u32_e32 v3, v17, v21
	v_min_u32_e32 v11, v19, v23
	v_min_u32_e32 v53, v49, v34
	v_max_u32_e32 v34, v49, v34
	v_min_u32_e32 v49, v46, v27
	v_min_u32_e32 v40, v38, v25
	v_max_u32_e32 v27, v46, v27
	v_max_u32_e32 v25, v38, v25
	v_min_u32_e32 v39, v33, v26
	v_min_u32_e32 v35, v31, v24
	v_max_u32_e32 v26, v33, v26
	v_max_u32_e32 v24, v31, v24
	v_max_u32_e32 v12, v16, v15
	v_min_u32_e32 v8, v16, v15
	v_min_u32_e32 v20, v1, v9
	v_min_u32_e32 v16, v3, v11
	v_min_u32_e32 v38, v27, v25
	v_min_u32_e32 v31, v26, v24
	v_max3_u32 v1, v1, v9, v38
	v_max3_u32 v9, v20, v27, v25
	v_max3_u32 v3, v3, v11, v31
	v_max3_u32 v11, v16, v26, v24
	ds_read_b128 v[24:27], v72 offset:192
	v_max_u32_e32 v5, v10, v14
	v_min_u32_e32 v10, v18, v22
	v_min_u32_e32 v46, v45, v30
	v_min_u32_e32 v37, v32, v28
	v_max_u32_e32 v30, v45, v30
	v_max_u32_e32 v28, v32, v28
	v_max_u32_e32 v14, v18, v22
	v_min_u32_e32 v18, v2, v10
	v_min_u32_e32 v32, v30, v28
	v_min_u32_e32 v44, v43, v29
	v_max_u32_e32 v29, v43, v29
	v_max3_u32 v2, v2, v10, v32
	v_max3_u32 v10, v18, v30, v28
	s_waitcnt lgkmcnt(0)
; __device__ __forceinline__ unsigned fkey(float f) { unsigned u = __float_as_uint(f); return (u & 0x80000000u) ? ~u : (u | 0x80000000u); }
; __device__ __forceinline__ void sort16_desc(unsigned (&a)[16]) {
; #pragma unroll
;   for (int k = 2; k <= 16; k <<= 1)
; #pragma unroll
;     for (int j = k >> 1; j > 0; j >>= 1)
; #pragma unroll
;       for (int i = 0; i < 16; ++i) {
;         const int l = i ^ j;
;         if (l > i) { if ((i & k) == 0) cswap_desc(a[i], a[l]); else cswap_desc(a[l], a[i]); }
;       }
; }
; template <bool SORT>
; __device__ __forceinline__ void merge16_desc(unsigned (&a)[16], const unsigned (&b)[16]) {
; #pragma unroll
;   for (int i = 0; i < 16; ++i) a[i] = a[i] > b[15 - i] ? a[i] : b[15 - i];
;   if (SORT) {
; #pragma unroll
;     for (int j = 8; j > 0; j >>= 1)
; #pragma unroll
;       for (int i = 0; i < 16; ++i) { const int l = i ^ j; if (l > i) cswap_desc(a[i], a[l]); }
;   }
; __device__ void phase_peer_select(const Params& p, char* lds) {
;     ...
;       for (int grp = 0; grp < 4; ++grp) {
;         unsigned G[16];
; #pragma unroll
;         for (int n4 = 0; n4 < 4; ++n4) {
;           const f32x4 v = *(const f32x4*)(sp + grp * 16 + n4 * 4);
;           const unsigned ib = (unsigned)(127 - (half * 64 + grp * 16 + n4 * 4));
; #pragma unroll
;           for (int e = 0; e < 4; ++e) G[n4 * 4 + e] = (fkey(v[e]) & ~127u) | (ib - e);
;         }
;         sort16_desc(G);
;         if (grp == 0) {
; #pragma unroll
;           for (int i = 0; i < 16; ++i) L[i] = G[i];
;         } else merge16_desc<true>(L, G);
	v_cmp_gt_i32_e32 vcc, 0, v24
	v_not_b32_e32 v28, v24
	v_or_b32_e32 v24, 0x80000000, v24
	v_min_u32_e32 v22, v0, v8
	v_min_u32_e32 v43, v34, v29
	v_cndmask_b32_e32 v24, v24, v28, vcc
	v_cmp_gt_i32_e32 vcc, 0, v25
	v_not_b32_e32 v28, v25
	v_or_b32_e32 v25, 0x80000000, v25
	v_max3_u32 v0, v0, v8, v43
	v_max3_u32 v8, v22, v34, v29
	v_cndmask_b32_e32 v25, v25, v28, vcc
	v_cmp_gt_i32_e32 vcc, 0, v27
	v_not_b32_e32 v29, v27
	v_or_b32_e32 v27, 0x80000000, v27
	v_cndmask_b32_e32 v27, v27, v29, vcc
	v_cmp_gt_i32_e32 vcc, 0, v26
	v_not_b32_e32 v29, v26
	v_or_b32_e32 v26, 0x80000000, v26
	v_cndmask_b32_e32 v26, v26, v29, vcc
	v_and_or_b32 v24, v24, s38, v126
	v_and_or_b32 v25, v25, s38, v127
	v_and_or_b32 v27, v27, s38, v128
	v_and_or_b32 v26, v26, s38, v129
	v_max_u32_e32 v28, v24, v25
	v_min_u32_e32 v29, v27, v26
	v_min_u32_e32 v31, v24, v25
	v_max_u32_e32 v32, v27, v26
	ds_read_b128 v[24:27], v72 offset:208
	v_max_u32_e32 v7, v17, v21
	v_max_u32_e32 v15, v19, v23
	v_min_u32_e32 v17, v7, v15
	v_min_u32_e32 v36, v39, v35
	v_max3_u32 v7, v7, v15, v36
	v_max3_u32 v15, v17, v39, v35
	s_waitcnt lgkmcnt(0)
	v_cmp_gt_i32_e32 vcc, 0, v27
	v_not_b32_e32 v35, v27
	v_or_b32_e32 v27, 0x80000000, v27
	v_cndmask_b32_e32 v27, v27, v35, vcc
	v_cmp_gt_i32_e32 vcc, 0, v26
	v_not_b32_e32 v35, v26
	v_or_b32_e32 v26, 0x80000000, v26
	v_cndmask_b32_e32 v26, v26, v35, vcc
	v_cmp_gt_i32_e32 vcc, 0, v24
	v_not_b32_e32 v36, v24
	v_or_b32_e32 v24, 0x80000000, v24
	v_cndmask_b32_e32 v24, v24, v36, vcc
	v_cmp_gt_i32_e32 vcc, 0, v25
	v_not_b32_e32 v36, v25
	v_or_b32_e32 v25, 0x80000000, v25
	v_cndmask_b32_e32 v25, v25, v36, vcc
	v_and_or_b32 v27, v27, s38, v130
	v_and_or_b32 v26, v26, s38, v131
	v_and_or_b32 v24, v24, s38, v132
	v_and_or_b32 v25, v25, s38, v133
	v_min_u32_e32 v19, v6, v14
	v_min_u32_e32 v41, v46, v37
	v_max_u32_e32 v35, v27, v26
	v_min_u32_e32 v36, v24, v25
	v_min_u32_e32 v26, v27, v26
	v_max_u32_e32 v24, v24, v25
	v_max3_u32 v6, v6, v14, v41
	v_max3_u32 v14, v19, v46, v37
	v_max_u32_e32 v30, v28, v29
	v_max_u32_e32 v33, v31, v32
	v_min_u32_e32 v37, v35, v36
	v_min_u32_e32 v25, v26, v24
	v_min_u32_e32 v27, v28, v29
	v_min_u32_e32 v28, v31, v32
	v_max_u32_e32 v31, v35, v36
	v_max_u32_e32 v24, v26, v24
	v_max_u32_e32 v34, v30, v33
	v_min_u32_e32 v38, v37, v25
	v_max_u32_e32 v29, v27, v28
	v_min_u32_e32 v32, v31, v24
	v_min_u32_e32 v30, v30, v33
	v_max_u32_e32 v33, v37, v25
	v_min_u32_e32 v28, v27, v28
	v_max_u32_e32 v31, v31, v24
	ds_read_b128 v[24:27], v72 offset:240
	v_min_u32_e32 v23, v4, v12
	v_min_u32_e32 v51, v53, v44
	v_max3_u32 v4, v4, v12, v51
	v_max3_u32 v12, v23, v53, v44
	s_waitcnt lgkmcnt(0)
	v_cmp_gt_i32_e32 vcc, 0, v27
	v_not_b32_e32 v43, v27
	v_or_b32_e32 v27, 0x80000000, v27
	v_cndmask_b32_e32 v27, v27, v43, vcc
	v_cmp_gt_i32_e32 vcc, 0, v26
	v_not_b32_e32 v43, v26
	v_or_b32_e32 v26, 0x80000000, v26
	v_cndmask_b32_e32 v26, v26, v43, vcc
	v_cmp_gt_i32_e32 vcc, 0, v24
	v_not_b32_e32 v44, v24
	v_or_b32_e32 v24, 0x80000000, v24
	v_cndmask_b32_e32 v24, v24, v44, vcc
	v_cmp_gt_i32_e32 vcc, 0, v25
	v_not_b32_e32 v44, v25
	v_or_b32_e32 v25, 0x80000000, v25
	v_cndmask_b32_e32 v25, v25, v44, vcc
	v_min_u32_e32 v47, v49, v40
	v_and_or_b32 v27, v27, s38, v134
	v_and_or_b32 v26, v26, s38, v135
	v_and_or_b32 v24, v24, s38, v136
	v_and_or_b32 v25, v25, s38, v137
	v_min_u32_e32 v21, v5, v13
	v_max3_u32 v5, v5, v13, v47
	v_max_u32_e32 v43, v27, v26
	v_min_u32_e32 v44, v24, v25
	v_min_u32_e32 v46, v27, v26
	v_max_u32_e32 v47, v24, v25
	ds_read_b128 v[24:27], v72 offset:224
	v_max_u32_e32 v45, v43, v44
	v_max_u32_e32 v48, v46, v47
	v_min_u32_e32 v43, v43, v44
	v_min_u32_e32 v44, v46, v47
	s_waitcnt lgkmcnt(0)
	v_cmp_gt_i32_e32 vcc, 0, v24
	v_not_b32_e32 v50, v24
	v_or_b32_e32 v24, 0x80000000, v24
	v_cndmask_b32_e32 v24, v24, v50, vcc
	v_cmp_gt_i32_e32 vcc, 0, v25
	v_not_b32_e32 v50, v25
	v_or_b32_e32 v25, 0x80000000, v25
	v_cndmask_b32_e32 v25, v25, v50, vcc
	v_cmp_gt_i32_e32 vcc, 0, v27
	v_not_b32_e32 v51, v27
	v_or_b32_e32 v27, 0x80000000, v27
	v_cndmask_b32_e32 v27, v27, v51, vcc
	v_cmp_gt_i32_e32 vcc, 0, v26
	v_not_b32_e32 v51, v26
	v_or_b32_e32 v26, 0x80000000, v26
	v_cndmask_b32_e32 v26, v26, v51, vcc
	v_and_or_b32 v24, v24, s38, v138
	v_and_or_b32 v25, v25, s38, v139
	v_and_or_b32 v27, v27, s38, v140
	v_and_or_b32 v26, v26, s38, v141
	v_max_u32_e32 v50, v24, v25
	v_min_u32_e32 v51, v27, v26
	v_min_u32_e32 v24, v24, v25
	v_max_u32_e32 v25, v27, v26
	v_min_u32_e32 v52, v50, v51
	v_min_u32_e32 v26, v24, v25
	v_max_u32_e32 v47, v50, v51
	v_max_u32_e32 v24, v24, v25
	v_max3_u32 v13, v21, v49, v40
	v_max_u32_e32 v49, v45, v48
	v_min_u32_e32 v27, v52, v26
	v_max_u32_e32 v46, v43, v44
	v_min_u32_e32 v25, v47, v24
	v_min_u32_e32 v45, v45, v48
	v_max_u32_e32 v26, v52, v26
	v_min_u32_e32 v43, v43, v44
	v_max_u32_e32 v24, v47, v24
	v_max_u32_e32 v39, v34, v38
	v_max_u32_e32 v35, v29, v32
	v_max_u32_e32 v37, v30, v33
	v_max_u32_e32 v40, v28, v31
	v_min_u32_e32 v53, v49, v27
	v_min_u32_e32 v50, v46, v25
	v_min_u32_e32 v48, v45, v26
	v_min_u32_e32 v44, v43, v24
	v_min_u32_e32 v34, v34, v38
	v_min_u32_e32 v29, v29, v32
	v_min_u32_e32 v30, v30, v33
	v_min_u32_e32 v28, v28, v31
	v_max_u32_e32 v27, v49, v27
	v_max_u32_e32 v25, v46, v25
	v_max_u32_e32 v26, v45, v26
	v_max_u32_e32 v24, v43, v24
	v_max_u32_e32 v36, v39, v35
	v_max_u32_e32 v41, v37, v40
	v_min_u32_e32 v51, v53, v50
	v_min_u32_e32 v47, v48, v44
	v_max_u32_e32 v32, v34, v29
	v_max_u32_e32 v31, v30, v28
	v_min_u32_e32 v38, v27, v25
	v_min_u32_e32 v43, v26, v24
	v_min_u32_e32 v35, v39, v35
	v_min_u32_e32 v37, v37, v40
	v_max_u32_e32 v40, v53, v50
	v_max_u32_e32 v44, v48, v44
	v_min_u32_e32 v29, v34, v29
; template <bool SORT>
; __device__ __forceinline__ void merge16_desc(unsigned (&a)[16], const unsigned (&b)[16]) {
; #pragma unroll
;   for (int i = 0; i < 16; ++i) a[i] = a[i] > b[15 - i] ? a[i] : b[15 - i];
;   if (SORT) {
; #pragma unroll
;     for (int j = 8; j > 0; j >>= 1)
; #pragma unroll
;       for (int i = 0; i < 16; ++i) { const int l = i ^ j; if (l > i) cswap_desc(a[i], a[l]); }
;   }
; __device__ void phase_peer_select(const Params& p, char* lds) {
;     ...
;         } else merge16_desc<true>(L, G);
;       }
;     }
;     __syncthreads();
;     if (half == 1) {
; #pragma unroll
;       for (int i = 0; i < 16; i += 4) { u32x4 w = {L[i], L[i + 1], L[i + 2], L[i + 3]}; *(u32x4*)(LH + (c * 64 + tok) * 20 + i) = w; }
;     }
	v_min_u32_e32 v28, v30, v28
	v_max_u32_e32 v25, v27, v25
	v_max_u32_e32 v24, v26, v24
	v_max_u32_e32 v42, v36, v41
	v_min_u32_e32 v52, v51, v47
	v_max_u32_e32 v33, v32, v31
	v_min_u32_e32 v45, v38, v43
	v_max_u32_e32 v39, v35, v37
	v_min_u32_e32 v48, v40, v44
	v_max_u32_e32 v30, v29, v28
	v_min_u32_e32 v26, v25, v24
	v_min_u32_e32 v36, v36, v41
	v_max_u32_e32 v41, v51, v47
	v_min_u32_e32 v31, v32, v31
	v_max_u32_e32 v32, v38, v43
	v_min_u32_e32 v35, v35, v37
	v_max_u32_e32 v37, v40, v44
	v_min_u32_e32 v28, v29, v28
	v_max_u32_e32 v24, v25, v24
	v_max_u32_e32 v16, v4, v6
	v_min_u32_e32 v4, v4, v6
	v_max_u32_e32 v6, v12, v14
	v_min_u32_e32 v12, v12, v14
	v_max_u32_e32 v14, v0, v2
	v_min_u32_e32 v0, v0, v2
	v_max_u32_e32 v2, v8, v10
	v_min_u32_e32 v8, v8, v10
	v_max_u32_e32 v10, v5, v7
	v_min_u32_e32 v5, v5, v7
	v_max_u32_e32 v7, v13, v15
	v_min_u32_e32 v13, v13, v15
	v_max_u32_e32 v15, v1, v3
	v_min_u32_e32 v1, v1, v3
	v_max_u32_e32 v3, v9, v11
	v_min_u32_e32 v9, v9, v11
	v_min_u32_e32 v54, v42, v52
	v_min_u32_e32 v46, v33, v45
	v_min_u32_e32 v50, v39, v48
	v_min_u32_e32 v27, v30, v26
	v_min_u32_e32 v47, v36, v41
	v_min_u32_e32 v38, v31, v32
	v_min_u32_e32 v40, v35, v37
	v_min_u32_e32 v25, v28, v24
	v_max_u32_e32 v42, v42, v52
	v_max_u32_e32 v33, v33, v45
	v_max_u32_e32 v39, v39, v48
	v_max_u32_e32 v26, v30, v26
	v_max_u32_e32 v36, v36, v41
	v_max_u32_e32 v31, v31, v32
	v_max_u32_e32 v35, v35, v37
	v_max_u32_e32 v24, v28, v24
	v_max_u32_e32 v11, v16, v10
	v_min_u32_e32 v10, v16, v10
	v_max_u32_e32 v16, v6, v7
	v_min_u32_e32 v6, v6, v7
	v_max_u32_e32 v7, v14, v15
	v_min_u32_e32 v14, v14, v15
	v_max_u32_e32 v15, v2, v3
	v_min_u32_e32 v2, v2, v3
	v_max_u32_e32 v3, v4, v5
	v_min_u32_e32 v17, v4, v5
	v_max_u32_e32 v18, v12, v13
	v_min_u32_e32 v19, v12, v13
	v_max_u32_e32 v20, v0, v1
	v_min_u32_e32 v21, v0, v1
	v_max_u32_e32 v22, v8, v9
	v_min_u32_e32 v23, v8, v9
	v_min_u32_e32 v49, v54, v46
	v_min_u32_e32 v34, v50, v27
	v_min_u32_e32 v43, v47, v38
	v_min_u32_e32 v29, v40, v25
	v_max_u32_e32 v46, v54, v46
	v_max_u32_e32 v27, v50, v27
	v_max_u32_e32 v38, v47, v38
	v_max_u32_e32 v25, v40, v25
	v_min_u32_e32 v45, v42, v33
	v_min_u32_e32 v30, v39, v26
	v_min_u32_e32 v32, v36, v31
	v_min_u32_e32 v28, v35, v24
	v_max_u32_e32 v33, v42, v33
	v_max_u32_e32 v26, v39, v26
	v_max_u32_e32 v31, v36, v31
	v_max_u32_e32 v24, v35, v24
	v_max_u32_e32 v4, v11, v7
	v_min_u32_e32 v0, v11, v7
	v_max_u32_e32 v12, v16, v15
	v_min_u32_e32 v8, v16, v15
	v_max_u32_e32 v5, v10, v14
	v_min_u32_e32 v1, v10, v14
	v_max_u32_e32 v13, v6, v2
	v_min_u32_e32 v9, v6, v2
	v_max_u32_e32 v6, v3, v20
	v_min_u32_e32 v2, v3, v20
	v_max_u32_e32 v14, v18, v22
	v_min_u32_e32 v10, v18, v22
	v_max_u32_e32 v7, v17, v21
	v_min_u32_e32 v3, v17, v21
	v_max_u32_e32 v15, v19, v23
	v_min_u32_e32 v11, v19, v23
	v_min_u32_e32 v53, v49, v34
	v_min_u32_e32 v44, v43, v29
	v_max_u32_e32 v34, v49, v34
	v_max_u32_e32 v29, v43, v29
	v_min_u32_e32 v49, v46, v27
	v_min_u32_e32 v40, v38, v25
	v_max_u32_e32 v27, v46, v27
	v_max_u32_e32 v25, v38, v25
	v_min_u32_e32 v46, v45, v30
	v_min_u32_e32 v37, v32, v28
	v_max_u32_e32 v30, v45, v30
	v_max_u32_e32 v28, v32, v28
	v_min_u32_e32 v39, v33, v26
	v_min_u32_e32 v35, v31, v24
	v_max_u32_e32 v26, v33, v26
	v_max_u32_e32 v24, v31, v24
	v_min_u32_e32 v23, v4, v12
	v_min_u32_e32 v22, v0, v8
	v_min_u32_e32 v21, v5, v13
	v_min_u32_e32 v20, v1, v9
	v_min_u32_e32 v19, v6, v14
	v_min_u32_e32 v18, v2, v10
	v_min_u32_e32 v17, v7, v15
	v_min_u32_e32 v16, v3, v11
	v_min_u32_e32 v51, v53, v44
	v_min_u32_e32 v43, v34, v29
	v_min_u32_e32 v47, v49, v40
	v_min_u32_e32 v38, v27, v25
	v_min_u32_e32 v41, v46, v37
	v_min_u32_e32 v32, v30, v28
	v_min_u32_e32 v36, v39, v35
	v_min_u32_e32 v31, v26, v24
	v_max3_u32 v4, v4, v12, v51
	v_max3_u32 v12, v23, v53, v44
	v_max3_u32 v0, v0, v8, v43
	v_max3_u32 v8, v22, v34, v29
	v_max3_u32 v5, v5, v13, v47
	v_max3_u32 v13, v21, v49, v40
	v_max3_u32 v1, v1, v9, v38
	v_max3_u32 v9, v20, v27, v25
	v_max3_u32 v6, v6, v14, v41
	v_max3_u32 v14, v19, v46, v37
	v_max3_u32 v2, v2, v10, v32
	v_max3_u32 v10, v18, v30, v28
	v_max3_u32 v7, v7, v15, v36
	v_max3_u32 v15, v17, v39, v35
	v_max3_u32 v3, v3, v11, v31
	v_max3_u32 v11, v16, v26, v24
	v_max_u32_e32 v16, v4, v6
	v_min_u32_e32 v4, v4, v6
	v_max_u32_e32 v6, v12, v14
	v_min_u32_e32 v12, v12, v14
	v_max_u32_e32 v14, v0, v2
	v_min_u32_e32 v0, v0, v2
	v_max_u32_e32 v2, v8, v10
	v_min_u32_e32 v8, v8, v10
	v_max_u32_e32 v10, v5, v7
	v_min_u32_e32 v5, v5, v7
	v_max_u32_e32 v7, v13, v15
	v_min_u32_e32 v13, v13, v15
	v_max_u32_e32 v15, v1, v3
	v_min_u32_e32 v1, v1, v3
	v_max_u32_e32 v3, v9, v11
	v_min_u32_e32 v9, v9, v11
	v_max_u32_e32 v11, v16, v10
	v_min_u32_e32 v10, v16, v10
	v_max_u32_e32 v16, v6, v7
	v_min_u32_e32 v6, v6, v7
	v_max_u32_e32 v7, v14, v15
	v_min_u32_e32 v14, v14, v15
	v_max_u32_e32 v15, v2, v3
	v_min_u32_e32 v2, v2, v3
	v_max_u32_e32 v3, v4, v5
	v_min_u32_e32 v4, v4, v5
	v_max_u32_e32 v5, v12, v13
	v_min_u32_e32 v12, v12, v13
	v_max_u32_e32 v13, v0, v1
	v_min_u32_e32 v0, v0, v1
	v_max_u32_e32 v1, v8, v9
	v_min_u32_e32 v8, v8, v9
	v_max_u32_e32 v9, v11, v7
	v_min_u32_e32 v7, v11, v7
	v_max_u32_e32 v11, v16, v15
	v_min_u32_e32 v15, v16, v15
	v_max_u32_e32 v16, v10, v14
	v_min_u32_e32 v10, v10, v14
	v_max_u32_e32 v14, v6, v2
	v_min_u32_e32 v17, v6, v2
	v_max_u32_e32 v18, v3, v13
	v_min_u32_e32 v13, v3, v13
	v_max_u32_e32 v19, v5, v1
	v_min_u32_e32 v20, v5, v1
	v_max_u32_e32 v21, v4, v0
	v_min_u32_e32 v22, v4, v0
	v_max_u32_e32 v23, v12, v8
	v_min_u32_e32 v8, v12, v8
	v_max_u32_e32 v0, v9, v11
	v_min_u32_e32 v1, v9, v11
	v_max_u32_e32 v2, v7, v15
	v_min_u32_e32 v3, v7, v15
	v_max_u32_e32 v4, v16, v14
	v_min_u32_e32 v5, v16, v14
	v_max_u32_e32 v6, v10, v17
	v_min_u32_e32 v7, v10, v17
	v_max_u32_e32 v17, v18, v19
	v_min_u32_e32 v16, v18, v19
	v_max_u32_e32 v15, v13, v20
	v_min_u32_e32 v14, v13, v20
	v_max_u32_e32 v13, v21, v23
	v_min_u32_e32 v12, v21, v23
	v_max_u32_e32 v10, v22, v8
	v_min_u32_e32 v11, v22, v8
	s_barrier
	s_and_saveexec_b64 s[0:1], s[42:43]
	s_cbranch_execz .LBB0_1096
	v_mov_b32_e32 v8, v13
	v_mov_b32_e32 v9, v12
	v_mov_b32_e32 v18, v17
	v_mov_b32_e32 v19, v16
	v_mov_b32_e32 v20, v15
	v_mov_b32_e32 v21, v14
	ds_write_b128 v73, v[0:3]
	ds_write_b128 v73, v[4:7] offset:16
	ds_write_b128 v73, v[18:21] offset:32
	ds_write_b128 v73, v[8:11] offset:48
